# v16: v15 + cache-panel conversion loop waits for the page-table word once ahead of the loop, so a trip's loads overlap the previous trip's stores
# baseline (speedup 1.0000x reference)
.LBB0_635:
	s_lshl_b64 s[10:11], s[94:95], 20
	s_add_u32 s0, s90, s10
	s_addc_u32 s1, s91, s11
	s_add_u32 s0, s0, 0x26d71600
	s_addc_u32 s1, s1, 0
	s_lshl_b32 s2, s94, 4
	s_and_b32 s2, s2, 0x7f0
	v_or_b32_e32 v0, s2, v219
	v_readlane_b32 s12, v239, 51
	v_lshlrev_b32_e32 v0, 2, v0
	v_readlane_b32 s13, v239, 52
	s_waitcnt vmcnt(0) lgkmcnt(0)
	s_barrier
	s_and_b32 s2, s87, 0xffffffc0
	v_add_u32_e32 v129, s2, v217
	s_nop 0
	global_load_dword v5, v0, s[12:13]
	s_lshl_b32 s2, s94, 1
	v_readlane_b32 s14, v239, 53
	v_readlane_b32 s15, v239, 54
	v_readlane_b32 s16, v239, 55
	v_readlane_b32 s17, v239, 56
	v_readlane_b32 s18, v239, 57
	v_readlane_b32 s19, v239, 58
	v_readlane_b32 s20, v239, 59
	v_readlane_b32 s21, v239, 60
	v_readlane_b32 s22, v239, 61
	v_readlane_b32 s23, v239, 62
	v_readlane_b32 s24, v239, 63
	v_readlane_b32 s25, v238, 0
	v_readlane_b32 s26, v238, 1
	v_readlane_b32 s27, v238, 2
	s_and_b32 s2, s2, 0xffffff00
	s_ashr_i32 s3, s2, 31
	v_readlane_b32 s12, v239, 3
	v_ashrrev_i32_e32 v128, 4, v129
	s_lshl_b64 s[2:3], s[2:3], 2
	v_readlane_b32 s20, v239, 11
	v_readlane_b32 s21, v239, 12
	s_add_u32 s2, s20, s2
	v_lshlrev_b32_e32 v0, 5, v128
	s_addc_u32 s3, s21, s3
	v_and_b32_e32 v2, 0x200, v0
	v_mov_b32_e32 v3, 0
	v_lshl_add_u64 v[0:1], s[2:3], 0, v[2:3]
	v_lshlrev_b32_e32 v2, 5, v219
	v_lshl_add_u64 v[0:1], v[0:1], 0, v[2:3]
	v_lshlrev_b32_e32 v2, 8, v128
	v_and_b32_e32 v2, 0xf00, v2
	v_lshl_add_u64 v[6:7], s[0:1], 0, v[2:3]
	v_lshlrev_b32_e32 v2, 4, v219
	v_lshl_add_u64 v[2:3], v[6:7], 0, v[2:3]
	v_lshrrev_b32_e32 v7, 1, v128
	v_and_b32_e32 v9, 15, v128
	v_and_b32_e32 v11, 0x70, v7
	s_movk_i32 s2, 0x70
	v_or_b32_e32 v4, v11, v9
	v_bitop3_b32 v12, v11, 64, v9 bitop3:0x36
	v_add_u32_e32 v11, 0x50, v7
	v_add_u32_e32 v6, 16, v7
	v_add_u32_e32 v8, 32, v7
	v_add_u32_e32 v10, 48, v7
	v_and_or_b32 v14, v11, s2, v9
	v_add_u32_e32 v11, 0x60, v7
	v_add_u32_e32 v7, 0x70, v7
	v_and_or_b32 v6, v6, s2, v9
	v_and_or_b32 v8, v8, s2, v9
	v_and_or_b32 v10, v10, s2, v9
	v_and_or_b32 v16, v11, s2, v9
	v_and_or_b32 v18, v7, s2, v9
	v_add_u32_e32 v7, 0x1e0, v128
	s_mov_b32 s8, 0
	v_readlane_b32 s13, v239, 4
	v_readlane_b32 s14, v239, 5
	v_readlane_b32 s15, v239, 6
	v_readlane_b32 s16, v239, 7
	v_readlane_b32 s17, v239, 8
	v_readlane_b32 s18, v239, 9
	v_readlane_b32 s19, v239, 10
	v_readlane_b32 s22, v239, 13
	v_readlane_b32 s23, v239, 14
	v_readlane_b32 s24, v239, 15
	v_readlane_b32 s25, v239, 16
	v_readlane_b32 s26, v239, 17
	v_readlane_b32 s27, v239, 18
	s_waitcnt vmcnt(0)
.LBB0_636:
	v_readlane_b32 s2, v5, s8
	s_add_i32 s3, s8, 1
	v_add_u32_e32 v11, 0xfffffe40, v7
	v_add_u32_e32 v19, 0xfffffec0, v7
	v_add_u32_e32 v21, 0xfffffee0, v7
	v_add_u32_e32 v27, 0xffffff40, v7
	v_subrev_u32_e32 v35, 64, v7
	v_ashrrev_i32_e32 v20, 4, v7
	v_readlane_b32 s12, v5, s3
	s_ashr_i32 s3, s2, 31
	v_add_u32_e32 v9, 0xfffffe20, v7
	v_add_u32_e32 v13, 0xfffffe60, v7
	v_add_u32_e32 v15, 0xfffffe80, v7
	v_add_u32_e32 v17, 0xfffffea0, v7
	v_add_u32_e32 v23, 0xffffff00, v7
	v_add_u32_e32 v25, 0xffffff20, v7
	v_add_u32_e32 v29, 0xffffff60, v7
	v_add_u32_e32 v31, 0xffffff80, v7
	v_add_u32_e32 v33, 0xffffffa0, v7
	v_subrev_u32_e32 v37, 32, v7
	v_ashrrev_i32_e32 v24, 4, v11
	v_ashrrev_i32_e32 v32, 4, v19
	v_ashrrev_i32_e32 v34, 4, v21
	v_ashrrev_i32_e32 v40, 4, v27
	v_ashrrev_i32_e32 v48, 4, v35
	v_ashrrev_i32_e32 v21, 31, v20
	s_lshl_b64 s[2:3], s[2:3], 7
	s_ashr_i32 s13, s12, 31
	v_ashrrev_i32_e32 v22, 4, v9
	v_ashrrev_i32_e32 v26, 4, v13
	v_ashrrev_i32_e32 v28, 4, v15
	v_ashrrev_i32_e32 v30, 4, v17
	v_ashrrev_i32_e32 v36, 4, v23
	v_ashrrev_i32_e32 v38, 4, v25
	v_ashrrev_i32_e32 v42, 4, v29
	v_ashrrev_i32_e32 v44, 4, v31
	v_ashrrev_i32_e32 v46, 4, v33
	v_ashrrev_i32_e32 v50, 4, v37
	v_ashrrev_i32_e32 v25, 31, v24
	v_ashrrev_i32_e32 v33, 31, v32
	v_ashrrev_i32_e32 v41, 31, v40
	v_ashrrev_i32_e32 v49, 31, v48
	v_lshlrev_b64 v[20:21], 12, v[20:21]
	v_mov_b32_e32 v53, s3
	v_or_b32_e32 v52, s2, v4
	v_mov_b32_e32 v55, s3
	v_or_b32_e32 v54, s2, v6
	v_mov_b32_e32 v57, s3
	v_or_b32_e32 v56, s2, v8
	v_mov_b32_e32 v59, s3
	v_or_b32_e32 v58, s2, v10
	v_mov_b32_e32 v61, s3
	v_or_b32_e32 v60, s2, v12
	v_mov_b32_e32 v63, s3
	v_or_b32_e32 v62, s2, v14
	v_mov_b32_e32 v65, s3
	v_or_b32_e32 v64, s2, v16
	v_mov_b32_e32 v67, s3
	v_or_b32_e32 v66, s2, v18
	s_lshl_b64 s[2:3], s[12:13], 7
	v_ashrrev_i32_e32 v23, 31, v22
	v_ashrrev_i32_e32 v27, 31, v26
	v_ashrrev_i32_e32 v29, 31, v28
	v_ashrrev_i32_e32 v31, 31, v30
	v_ashrrev_i32_e32 v35, 31, v34
	v_ashrrev_i32_e32 v37, 31, v36
	v_ashrrev_i32_e32 v39, 31, v38
	v_ashrrev_i32_e32 v43, 31, v42
	v_ashrrev_i32_e32 v45, 31, v44
	v_ashrrev_i32_e32 v47, 31, v46
	v_ashrrev_i32_e32 v51, 31, v50
	v_lshlrev_b64 v[24:25], 12, v[24:25]
	v_lshlrev_b64 v[32:33], 12, v[32:33]
	v_lshlrev_b64 v[40:41], 12, v[40:41]
	v_lshlrev_b64 v[48:49], 12, v[48:49]
	v_lshl_add_u64 v[150:151], v[2:3], 0, v[20:21]
	v_lshlrev_b64 v[20:21], 11, v[52:53]
	v_lshlrev_b64 v[52:53], 11, v[54:55]
	v_lshlrev_b64 v[54:55], 11, v[56:57]
	v_lshlrev_b64 v[56:57], 11, v[58:59]
	v_lshlrev_b64 v[58:59], 11, v[60:61]
	v_lshlrev_b64 v[60:61], 11, v[62:63]
	v_lshlrev_b64 v[62:63], 11, v[64:65]
	v_lshlrev_b64 v[64:65], 11, v[66:67]
	v_mov_b32_e32 v67, s3
	v_or_b32_e32 v66, s2, v4
	v_mov_b32_e32 v69, s3
	v_or_b32_e32 v68, s2, v6
	v_mov_b32_e32 v71, s3
	v_or_b32_e32 v70, s2, v8
	v_mov_b32_e32 v73, s3
	v_or_b32_e32 v72, s2, v10
	v_mov_b32_e32 v75, s3
	v_or_b32_e32 v74, s2, v12
	v_mov_b32_e32 v77, s3
	v_or_b32_e32 v76, s2, v14
	v_mov_b32_e32 v79, s3
	v_or_b32_e32 v78, s2, v16
	v_mov_b32_e32 v81, s3
	v_or_b32_e32 v80, s2, v18
	v_lshlrev_b64 v[22:23], 12, v[22:23]
	v_lshlrev_b64 v[26:27], 12, v[26:27]
	v_lshlrev_b64 v[28:29], 12, v[28:29]
	v_lshlrev_b64 v[30:31], 12, v[30:31]
	v_lshlrev_b64 v[34:35], 12, v[34:35]
	v_lshlrev_b64 v[36:37], 12, v[36:37]
	v_lshlrev_b64 v[38:39], 12, v[38:39]
	v_lshlrev_b64 v[42:43], 12, v[42:43]
	v_lshlrev_b64 v[44:45], 12, v[44:45]
	v_lshlrev_b64 v[46:47], 12, v[46:47]
	v_lshlrev_b64 v[50:51], 12, v[50:51]
	v_lshl_add_u64 v[154:155], v[2:3], 0, v[24:25]
	v_lshl_add_u64 v[162:163], v[2:3], 0, v[32:33]
	v_lshl_add_u64 v[170:171], v[2:3], 0, v[40:41]
	v_lshl_add_u64 v[178:179], v[2:3], 0, v[48:49]
	v_lshl_add_u64 v[24:25], v[0:1], 0, v[20:21]
	v_lshl_add_u64 v[32:33], v[0:1], 0, v[52:53]
	v_lshl_add_u64 v[40:41], v[0:1], 0, v[54:55]
	v_lshl_add_u64 v[48:49], v[0:1], 0, v[56:57]
	v_lshl_add_u64 v[56:57], v[0:1], 0, v[58:59]
	v_lshl_add_u64 v[82:83], v[0:1], 0, v[60:61]
	v_lshlrev_b64 v[88:89], 11, v[66:67]
	v_lshlrev_b64 v[90:91], 11, v[68:69]
	v_lshlrev_b64 v[92:93], 11, v[70:71]
	v_lshlrev_b64 v[94:95], 11, v[72:73]
	v_lshlrev_b64 v[96:97], 11, v[74:75]
	v_lshlrev_b64 v[98:99], 11, v[76:77]
	v_lshlrev_b64 v[100:101], 11, v[78:79]
	v_lshlrev_b64 v[102:103], 11, v[80:81]
	v_lshl_add_u64 v[152:153], v[2:3], 0, v[22:23]
	v_lshl_add_u64 v[156:157], v[2:3], 0, v[26:27]
	v_lshl_add_u64 v[158:159], v[2:3], 0, v[28:29]
	v_lshl_add_u64 v[160:161], v[2:3], 0, v[30:31]
	v_lshl_add_u64 v[164:165], v[2:3], 0, v[34:35]
	v_lshl_add_u64 v[166:167], v[2:3], 0, v[36:37]
	v_lshl_add_u64 v[168:169], v[2:3], 0, v[38:39]
	v_lshl_add_u64 v[172:173], v[2:3], 0, v[42:43]
	v_lshl_add_u64 v[174:175], v[2:3], 0, v[44:45]
	v_lshl_add_u64 v[176:177], v[2:3], 0, v[46:47]
	v_lshl_add_u64 v[180:181], v[2:3], 0, v[50:51]
	v_lshl_add_u64 v[84:85], v[0:1], 0, v[62:63]
	v_lshl_add_u64 v[86:87], v[0:1], 0, v[64:65]
	global_load_dwordx4 v[20:23], v[24:25], off
	s_nop 0
	global_load_dwordx4 v[24:27], v[24:25], off offset:16
	s_nop 0
	global_load_dwordx4 v[28:31], v[32:33], off
	s_nop 0
	global_load_dwordx4 v[32:35], v[32:33], off offset:16
	s_nop 0
	global_load_dwordx4 v[36:39], v[40:41], off
	s_nop 0
	global_load_dwordx4 v[40:43], v[40:41], off offset:16
	s_nop 0
	global_load_dwordx4 v[44:47], v[48:49], off
	s_nop 0
	global_load_dwordx4 v[48:51], v[48:49], off offset:16
	s_nop 0
	global_load_dwordx4 v[52:55], v[56:57], off
	s_nop 0
	global_load_dwordx4 v[56:59], v[56:57], off offset:16
	s_nop 0
	global_load_dwordx4 v[60:63], v[82:83], off
	global_load_dwordx4 v[64:67], v[82:83], off offset:16
	global_load_dwordx4 v[68:71], v[84:85], off
	global_load_dwordx4 v[72:75], v[84:85], off offset:16
	global_load_dwordx4 v[76:79], v[86:87], off
	s_nop 0
	global_load_dwordx4 v[80:83], v[86:87], off offset:16
	v_lshl_add_u64 v[88:89], v[0:1], 0, v[88:89]
	v_lshl_add_u64 v[104:105], v[0:1], 0, v[90:91]
	v_lshl_add_u64 v[106:107], v[0:1], 0, v[92:93]
	v_lshl_add_u64 v[112:113], v[0:1], 0, v[94:95]
	v_lshl_add_u64 v[120:121], v[0:1], 0, v[96:97]
	v_lshl_add_u64 v[130:131], v[0:1], 0, v[98:99]
	v_lshl_add_u64 v[138:139], v[0:1], 0, v[100:101]
	v_lshl_add_u64 v[146:147], v[0:1], 0, v[102:103]
	global_load_dwordx4 v[84:87], v[88:89], off
	s_nop 0
	global_load_dwordx4 v[88:91], v[88:89], off offset:16
	s_nop 0
	global_load_dwordx4 v[92:95], v[104:105], off
	global_load_dwordx4 v[96:99], v[104:105], off offset:16
	global_load_dwordx4 v[100:103], v[106:107], off
	s_nop 0
	global_load_dwordx4 v[104:107], v[106:107], off offset:16
	s_nop 0
	global_load_dwordx4 v[108:111], v[112:113], off
	s_nop 0
	global_load_dwordx4 v[112:115], v[112:113], off offset:16
	s_nop 0
	global_load_dwordx4 v[116:119], v[120:121], off
	s_nop 0
	global_load_dwordx4 v[120:123], v[120:121], off offset:16
	s_nop 0
	global_load_dwordx4 v[124:127], v[130:131], off
	s_nop 0
	global_load_dwordx4 v[130:133], v[130:131], off offset:16
	s_nop 0
	global_load_dwordx4 v[134:137], v[138:139], off
	s_nop 0
	global_load_dwordx4 v[138:141], v[138:139], off offset:16
	s_nop 0
	global_load_dwordx4 v[142:145], v[146:147], off
	s_nop 0
	global_load_dwordx4 v[146:149], v[146:147], off offset:16
	s_add_i32 s9, s8, 2
	v_add_u32_e32 v7, 0x200, v7
	s_cmp_lt_u32 s8, 14
	s_mov_b32 s8, s9
	s_waitcnt vmcnt(31)
	v_cvt_pk_bf16_f32 v20, v20, v21
	v_cvt_pk_bf16_f32 v21, v22, v23
	s_waitcnt vmcnt(30)
	v_cvt_pk_bf16_f32 v22, v24, v25
	v_cvt_pk_bf16_f32 v23, v26, v27
	s_waitcnt vmcnt(29)
	v_cvt_pk_bf16_f32 v24, v28, v29
	v_cvt_pk_bf16_f32 v25, v30, v31
	s_waitcnt vmcnt(28)
	v_cvt_pk_bf16_f32 v26, v32, v33
	v_cvt_pk_bf16_f32 v27, v34, v35
	s_waitcnt vmcnt(27)
	v_cvt_pk_bf16_f32 v28, v36, v37
	v_cvt_pk_bf16_f32 v29, v38, v39
	s_waitcnt vmcnt(26)
	v_cvt_pk_bf16_f32 v30, v40, v41
	v_cvt_pk_bf16_f32 v31, v42, v43
	s_waitcnt vmcnt(25)
	v_cvt_pk_bf16_f32 v32, v44, v45
	v_cvt_pk_bf16_f32 v33, v46, v47
	s_waitcnt vmcnt(24)
	v_cvt_pk_bf16_f32 v34, v48, v49
	v_cvt_pk_bf16_f32 v35, v50, v51
	s_waitcnt vmcnt(23)
	v_cvt_pk_bf16_f32 v36, v52, v53
	v_cvt_pk_bf16_f32 v37, v54, v55
	s_waitcnt vmcnt(22)
	v_cvt_pk_bf16_f32 v38, v56, v57
	v_cvt_pk_bf16_f32 v39, v58, v59
	s_waitcnt vmcnt(21)
	v_cvt_pk_bf16_f32 v40, v60, v61
	v_cvt_pk_bf16_f32 v41, v62, v63
	s_waitcnt vmcnt(20)
	v_cvt_pk_bf16_f32 v42, v64, v65
	v_cvt_pk_bf16_f32 v43, v66, v67
	s_waitcnt vmcnt(19)
	v_cvt_pk_bf16_f32 v44, v68, v69
	v_cvt_pk_bf16_f32 v45, v70, v71
	s_waitcnt vmcnt(18)
	v_cvt_pk_bf16_f32 v46, v72, v73
	v_cvt_pk_bf16_f32 v47, v74, v75
	s_waitcnt vmcnt(17)
	v_cvt_pk_bf16_f32 v48, v76, v77
	v_cvt_pk_bf16_f32 v49, v78, v79
	s_waitcnt vmcnt(16)
	v_cvt_pk_bf16_f32 v50, v80, v81
	v_cvt_pk_bf16_f32 v51, v82, v83
	global_store_dwordx4 v[152:153], v[20:23], off
	global_store_dwordx4 v[154:155], v[24:27], off
	global_store_dwordx4 v[156:157], v[28:31], off
	global_store_dwordx4 v[158:159], v[32:35], off
	global_store_dwordx4 v[160:161], v[36:39], off
	global_store_dwordx4 v[162:163], v[40:43], off
	global_store_dwordx4 v[164:165], v[44:47], off
	global_store_dwordx4 v[166:167], v[48:51], off
	s_waitcnt vmcnt(23)
	v_cvt_pk_bf16_f32 v20, v84, v85
	v_cvt_pk_bf16_f32 v21, v86, v87
	s_waitcnt vmcnt(22)
	v_cvt_pk_bf16_f32 v22, v88, v89
	v_cvt_pk_bf16_f32 v23, v90, v91
	s_waitcnt vmcnt(21)
	v_cvt_pk_bf16_f32 v24, v92, v93
	v_cvt_pk_bf16_f32 v25, v94, v95
	s_waitcnt vmcnt(20)
	v_cvt_pk_bf16_f32 v26, v96, v97
	v_cvt_pk_bf16_f32 v27, v98, v99
	s_waitcnt vmcnt(19)
	v_cvt_pk_bf16_f32 v28, v100, v101
	v_cvt_pk_bf16_f32 v29, v102, v103
	s_waitcnt vmcnt(18)
	v_cvt_pk_bf16_f32 v30, v104, v105
	v_cvt_pk_bf16_f32 v31, v106, v107
	s_waitcnt vmcnt(17)
	v_cvt_pk_bf16_f32 v32, v108, v109
	v_cvt_pk_bf16_f32 v33, v110, v111
	s_waitcnt vmcnt(16)
	v_cvt_pk_bf16_f32 v34, v112, v113
	v_cvt_pk_bf16_f32 v35, v114, v115
	s_waitcnt vmcnt(15)
	v_cvt_pk_bf16_f32 v36, v116, v117
	v_cvt_pk_bf16_f32 v37, v118, v119
	s_waitcnt vmcnt(14)
	v_cvt_pk_bf16_f32 v38, v120, v121
	v_cvt_pk_bf16_f32 v39, v122, v123
	s_waitcnt vmcnt(13)
	v_cvt_pk_bf16_f32 v40, v124, v125
	v_cvt_pk_bf16_f32 v41, v126, v127
	s_waitcnt vmcnt(12)
	v_cvt_pk_bf16_f32 v42, v130, v131
	v_cvt_pk_bf16_f32 v43, v132, v133
	s_waitcnt vmcnt(11)
	v_cvt_pk_bf16_f32 v44, v134, v135
	v_cvt_pk_bf16_f32 v45, v136, v137
	s_waitcnt vmcnt(10)
	v_cvt_pk_bf16_f32 v46, v138, v139
	v_cvt_pk_bf16_f32 v47, v140, v141
	s_waitcnt vmcnt(9)
	v_cvt_pk_bf16_f32 v48, v142, v143
	v_cvt_pk_bf16_f32 v49, v144, v145
	s_waitcnt vmcnt(8)
	v_cvt_pk_bf16_f32 v50, v146, v147
	v_cvt_pk_bf16_f32 v51, v148, v149
	global_store_dwordx4 v[168:169], v[20:23], off
	global_store_dwordx4 v[170:171], v[24:27], off
	global_store_dwordx4 v[172:173], v[28:31], off
	global_store_dwordx4 v[174:175], v[32:35], off
	global_store_dwordx4 v[176:177], v[36:39], off
	global_store_dwordx4 v[178:179], v[40:43], off
	global_store_dwordx4 v[180:181], v[44:47], off
	global_store_dwordx4 v[150:151], v[48:51], off
	s_cbranch_scc1 .LBB0_636
	v_readlane_b32 s3, v238, 3
	s_lshl_b32 s12, s3, 10
	v_add_u32_e32 v138, s12, v224
	v_ashrrev_i32_e32 v0, 31, v138
	v_lshrrev_b32_e32 v0, 22, v0
	v_add_u32_e32 v0, v138, v0
	v_ashrrev_i32_e32 v142, 10, v0
	v_mul_i32_i24_e32 v0, 0x400, v142
	v_sub_u32_e32 v0, v138, v0
	v_lshrrev_b32_e32 v1, 4, v0
	v_bitop3_b32 v0, v1, v0, 32 bitop3:0x6c
	v_ashrrev_i32_e32 v2, 31, v0
	v_lshrrev_b32_e32 v2, 26, v2
	v_add_u32_e32 v2, v0, v2
	v_ashrrev_i32_e32 v8, 6, v2
	v_and_b32_e32 v2, 0xc0, v2
	v_sub_u32_e32 v0, v0, v2
	v_mov_b32_e32 v2, 1
	v_lshlrev_b32_e32 v143, 3, v142
	v_lshlrev_b32_e32 v3, 5, v142
	v_ashrrev_i16_sdwa v0, v2, sext(v0) dst_sel:DWORD dst_unused:UNUSED_PAD src0_sel:DWORD src1_sel:BYTE_0
	v_and_b32_e32 v1, 0xffff0, v143
	v_and_b32_e32 v141, 32, v3
	v_bfe_i32 v10, v0, 0, 16
	v_add_u32_e32 v0, v141, v10
	v_add_lshl_u32 v1, v8, v1, 12
	v_lshl_add_u32 v130, v0, 1, v1
	v_add_u32_e32 v0, 0x2000, v138
	v_ashrrev_i32_e32 v1, 31, v0
	v_lshrrev_b32_e32 v1, 22, v1
	v_add_u32_e32 v1, v0, v1
	v_ashrrev_i32_e32 v9, 10, v1
	v_mul_i32_i24_e32 v1, 0x400, v9
	v_sub_u32_e32 v0, v0, v1
	v_lshrrev_b32_e32 v1, 4, v0
	v_bitop3_b32 v0, v1, v0, 32 bitop3:0x6c
	v_ashrrev_i32_e32 v3, 31, v0
	v_lshrrev_b32_e32 v3, 26, v3
	s_ashr_i32 s2, s94, 7
	v_add_u32_e32 v3, v0, v3
	v_ashrrev_i32_e32 v11, 6, v3
	v_and_b32_e32 v3, 0xffc0, v3
	s_ashr_i32 s16, s3, 2
	s_ashr_i32 s3, s2, 31
	v_sub_u32_e32 v0, v0, v3
	s_lshl_b64 s[2:3], s[2:3], 20
	v_lshrrev_b16_e32 v3, 7, v0
	s_add_u32 s8, s90, s2
	v_and_b32_e32 v3, 1, v3
	s_addc_u32 s9, s91, s3
	v_add_u16_e32 v0, v0, v3
	s_add_u32 s2, s8, 0x37771600
	v_lshlrev_b32_e32 v1, 3, v9
	v_lshlrev_b32_e32 v4, 5, v9
	v_ashrrev_i16_sdwa v0, v2, sext(v0) dst_sel:DWORD dst_unused:UNUSED_PAD src0_sel:DWORD src1_sel:BYTE_0
	s_addc_u32 s3, s9, 0
	s_add_i32 s69, s12, 0
	v_and_b32_e32 v1, 0xffff0, v1
	v_and_b32_e32 v4, 32, v4
	v_bfe_i32 v12, v0, 0, 16
	s_add_i32 s25, s69, 0x10000
	v_add_u32_e32 v0, v4, v12
	v_add_lshl_u32 v1, v11, v1, 12
	s_mov_b32 m0, s25
	s_add_i32 s19, s69, 0x12000
	s_barrier
	v_lshl_add_u32 v132, v0, 1, v1
	global_load_lds_dwordx4 v130, s[2:3]
	s_mov_b32 m0, s19
	s_add_i32 s70, s69, 0x2000
	global_load_lds_dwordx4 v132, s[2:3]
	s_mov_b32 m0, s69
	s_add_u32 s8, s8, 0x377f1600
	global_load_lds_dwordx4 v130, s[0:1]
	s_mov_b32 m0, s70
	s_addc_u32 s9, s9, 0
	s_add_i32 s17, s69, 0x14000
	global_load_lds_dwordx4 v132, s[0:1]
	s_mov_b32 m0, s17
	s_add_i32 s18, s69, 0x16000
	global_load_lds_dwordx4 v130, s[8:9]
	s_mov_b32 m0, s18
	v_mov_b32_e32 v131, 0
	global_load_lds_dwordx4 v132, s[8:9]
	s_add_u32 s8, s0, 0x80000
	s_addc_u32 s9, s1, 0
	s_add_i32 s71, s69, 0x4000
	s_mov_b32 m0, s71
	s_add_i32 s72, s69, 0x6000
	global_load_lds_dwordx4 v130, s[8:9]
	s_mov_b32 m0, s72
	v_mov_b32_e32 v133, v131
	global_load_lds_dwordx4 v132, s[8:9]
	v_lshl_add_u64 v[6:7], s[2:3], 0, v[130:131]
	v_lshl_add_u64 v[4:5], s[2:3], 0, v[132:133]
	v_lshl_add_u64 v[2:3], s[0:1], 0, v[130:131]
	s_cmp_lg_u32 s16, 1
	v_lshl_add_u64 v[0:1], s[0:1], 0, v[132:133]
	s_cbranch_scc1 .LBB0_639
	s_barrier
